# adds: in-proj epilogue fetches both bias halves up front (no mid-epilogue store drain)
# speedup vs baseline: 1.0199x; 1.0007x over previous
.LBB0_295:
	global_load_dwordx4 v[132:135], v[176:177], off
	global_load_dwordx4 v[128:131], v[176:177], off offset:16
	global_load_dwordx4 v[216:219], v[176:177], off offset:512
	global_load_dwordx4 v[220:223], v[176:177], off offset:528
	s_cmp_gt_i32 s25, 43
	s_cselect_b64 s[10:11], -1, 0
	v_cndmask_b32_e64 v136, 0, 1, s[10:11]
	s_cmp_lt_i32 s25, 52
	v_readfirstlane_b32 s10, v136
	s_cselect_b32 s12, s10, 2
	s_cmp_gt_i32 s12, 1
	s_mov_b64 s[10:11], -1
	s_waitcnt vmcnt(2)
	v_pk_add_f32 v[138:139], v[126:127], v[134:135]
	v_pk_add_f32 v[142:143], v[124:125], v[132:133]
	v_pk_add_f32 v[136:137], v[122:123], v[130:131]
	v_pk_add_f32 v[140:141], v[120:121], v[128:129]
	s_cbranch_scc0 .LBB0_297
	v_mul_f32_e32 v156, 0xbfb8aa3b, v138
	v_exp_f32_e32 v156, v156
	v_mul_f32_e32 v158, 0xbfb8aa3b, v136
	v_exp_f32_e32 v158, v158
	v_mul_f32_e32 v144, 0xbfb8aa3b, v142
	v_add_f32_e32 v156, 1.0, v156
	v_rcp_f32_e32 v179, v156
	v_add_f32_e32 v156, 1.0, v158
	v_mul_f32_e32 v158, 0xbfb8aa3b, v139
	v_mul_f32_e32 v145, 0xbfb8aa3b, v140
	v_mul_f32_e32 v146, 0xbfb8aa3b, v143
	v_mul_f32_e32 v147, 0xbfb8aa3b, v141
	v_exp_f32_e32 v158, v158
	v_mul_f32_e32 v159, 0xbfb8aa3b, v137
	v_exp_f32_e32 v144, v144
	v_exp_f32_e32 v145, v145
	v_exp_f32_e32 v146, v146
	v_exp_f32_e32 v147, v147
	v_exp_f32_e32 v159, v159
	v_rcp_f32_e32 v180, v156
	v_add_f32_e32 v156, 1.0, v158
	v_add_f32_e32 v144, 1.0, v144
	v_add_f32_e32 v145, 1.0, v145
	v_add_f32_e32 v146, 1.0, v146
	v_add_f32_e32 v147, 1.0, v147
	v_rcp_f32_e32 v207, v156
	v_add_f32_e32 v156, 1.0, v159
	v_rcp_f32_e32 v144, v144
	v_rcp_f32_e32 v145, v145
	v_rcp_f32_e32 v146, v146
	v_rcp_f32_e32 v147, v147
	v_rcp_f32_e32 v181, v156
	s_mov_b64 s[10:11], 0

.LBB0_343:
	v_lshl_add_u64 v[138:139], v[138:139], 0, s[52:53]
	v_cvt_pk_bf16_f32 v128, v140, v142
	v_cvt_pk_bf16_f32 v129, v144, v147
	v_cvt_pk_bf16_f32 v130, v141, v143
	v_cvt_pk_bf16_f32 v131, v145, v146
	global_store_dwordx4 v[138:139], v[128:131], off
	s_cmp_gt_i32 s12, 1
	s_mov_b64 s[8:9], -1
	s_waitcnt vmcnt(8)
	v_pk_add_f32 v[142:143], v[70:71], v[218:219]
	v_pk_add_f32 v[146:147], v[68:69], v[216:217]
	v_pk_add_f32 v[140:141], v[66:67], v[222:223]
	v_pk_add_f32 v[144:145], v[64:65], v[220:221]
	s_cbranch_scc0 .LBB0_345
	v_mul_f32_e32 v158, 0xbfb8aa3b, v144
	v_exp_f32_e32 v158, v158
	v_mul_f32_e32 v159, 0xbfb8aa3b, v147
	v_exp_f32_e32 v159, v159
	v_mul_f32_e32 v160, 0xbfb8aa3b, v145
	v_exp_f32_e32 v160, v160
	v_add_f32_e32 v158, 1.0, v158
	v_rcp_f32_e32 v179, v158
	v_add_f32_e32 v158, 1.0, v159
	v_mul_f32_e32 v159, 0xbfb8aa3b, v142
	v_rcp_f32_e32 v180, v158
	v_add_f32_e32 v158, 1.0, v160
	v_exp_f32_e32 v159, v159
	v_mul_f32_e32 v160, 0xbfb8aa3b, v140
	v_exp_f32_e32 v160, v160
	v_rcp_f32_e32 v181, v158
	v_add_f32_e32 v158, 1.0, v159
	v_mul_f32_e32 v159, 0xbfb8aa3b, v143
	v_mul_f32_e32 v156, 0xbfb8aa3b, v146
	v_rcp_f32_e32 v207, v158
	v_add_f32_e32 v158, 1.0, v160
	v_exp_f32_e32 v159, v159
	v_mul_f32_e32 v160, 0xbfb8aa3b, v141
	v_exp_f32_e32 v156, v156
	v_exp_f32_e32 v160, v160
	v_rcp_f32_e32 v208, v158
	v_add_f32_e32 v158, 1.0, v159
	v_add_f32_e32 v156, 1.0, v156
	v_rcp_f32_e32 v210, v158
	v_add_f32_e32 v158, 1.0, v160
	v_rcp_f32_e32 v156, v156
	v_rcp_f32_e32 v209, v158
	s_mov_b64 s[8:9], 0

.LBB0_349:
	v_cvt_pk_bf16_f32 v140, v156, v180
	v_cvt_pk_bf16_f32 v141, v207, v210
	v_cvt_pk_bf16_f32 v142, v179, v181
	v_cvt_pk_bf16_f32 v143, v208, v209
	global_store_dwordx4 v[136:137], v[140:143], off offset:256
	v_pk_add_f32 v[136:137], v[54:55], v[218:219]
	v_pk_add_f32 v[144:145], v[48:49], v[220:221]
	v_pk_add_f32 v[140:141], v[52:53], v[216:217]
	v_pk_add_f32 v[142:143], v[50:51], v[222:223]
	s_cmp_gt_i32 s12, 1
	s_mov_b64 s[8:9], -1
	s_cbranch_scc0 .LBB0_351
	v_mul_f32_e32 v158, 0xbfb8aa3b, v145
	v_exp_f32_e32 v158, v158
	v_mul_f32_e32 v159, 0xbfb8aa3b, v136
	v_exp_f32_e32 v159, v159
	v_mul_f32_e32 v160, 0xbfb8aa3b, v142
	v_exp_f32_e32 v160, v160
	v_add_f32_e32 v158, 1.0, v158
	v_rcp_f32_e32 v179, v158
	v_add_f32_e32 v158, 1.0, v159
	v_mul_f32_e32 v159, 0xbfb8aa3b, v137
	v_mul_f32_e32 v146, 0xbfb8aa3b, v140
	v_mul_f32_e32 v147, 0xbfb8aa3b, v144
	v_mul_f32_e32 v156, 0xbfb8aa3b, v141
	v_rcp_f32_e32 v180, v158
	v_add_f32_e32 v158, 1.0, v160
	v_exp_f32_e32 v159, v159
	v_mul_f32_e32 v160, 0xbfb8aa3b, v143
	v_exp_f32_e32 v146, v146
	v_exp_f32_e32 v147, v147
	v_exp_f32_e32 v156, v156
	v_exp_f32_e32 v160, v160
	v_rcp_f32_e32 v181, v158
	v_add_f32_e32 v158, 1.0, v159
	v_add_f32_e32 v146, 1.0, v146
	v_add_f32_e32 v147, 1.0, v147
	v_add_f32_e32 v156, 1.0, v156
	v_rcp_f32_e32 v208, v158
	v_add_f32_e32 v158, 1.0, v160
	v_rcp_f32_e32 v146, v146
	v_rcp_f32_e32 v147, v147
	v_rcp_f32_e32 v156, v156
	v_rcp_f32_e32 v207, v158
	s_mov_b64 s[8:9], 0

.LBB0_355:
	v_mad_u64_u32 v[136:137], s[8:9], s54, v202, v[138:139]
	s_mul_i32 s8, s55, 0xfffffec0
	s_sub_i32 s8, s8, s54
	v_cvt_pk_bf16_f32 v140, v146, v156
	v_cvt_pk_bf16_f32 v141, v180, v208
	v_cvt_pk_bf16_f32 v142, v147, v179
	v_cvt_pk_bf16_f32 v143, v181, v207
	v_add_u32_e32 v137, s8, v137
	global_store_dwordx4 v[136:137], v[140:143], off offset:256
	v_pk_add_f32 v[138:139], v[46:47], v[218:219]
	v_pk_add_f32 v[144:145], v[40:41], v[220:221]
	v_pk_add_f32 v[140:141], v[44:45], v[216:217]
	v_pk_add_f32 v[142:143], v[42:43], v[222:223]
	s_cmp_gt_i32 s12, 1
	s_mov_b64 s[8:9], -1
	s_movk_i32 s55, 0xfff
	s_mov_b32 s54, 0xf0c0
	s_cbranch_scc0 .LBB0_357
	v_mul_f32_e32 v158, 0xbfb8aa3b, v145
	v_exp_f32_e32 v158, v158
	v_mul_f32_e32 v159, 0xbfb8aa3b, v138
	v_exp_f32_e32 v159, v159
	v_mul_f32_e32 v160, 0xbfb8aa3b, v142
	v_exp_f32_e32 v160, v160
	v_add_f32_e32 v158, 1.0, v158
	v_rcp_f32_e32 v179, v158
	v_add_f32_e32 v158, 1.0, v159
	v_mul_f32_e32 v159, 0xbfb8aa3b, v139
	v_mul_f32_e32 v146, 0xbfb8aa3b, v140
	v_mul_f32_e32 v147, 0xbfb8aa3b, v144
	v_mul_f32_e32 v156, 0xbfb8aa3b, v141
	v_rcp_f32_e32 v180, v158
	v_add_f32_e32 v158, 1.0, v160
	v_exp_f32_e32 v159, v159
	v_mul_f32_e32 v160, 0xbfb8aa3b, v143
	v_exp_f32_e32 v146, v146
	v_exp_f32_e32 v147, v147
	v_exp_f32_e32 v156, v156
	v_exp_f32_e32 v160, v160
	v_rcp_f32_e32 v181, v158
	v_add_f32_e32 v158, 1.0, v159
	v_add_f32_e32 v146, 1.0, v146
	v_add_f32_e32 v147, 1.0, v147
	v_add_f32_e32 v156, 1.0, v156
	v_rcp_f32_e32 v208, v158
	v_add_f32_e32 v158, 1.0, v160
	v_rcp_f32_e32 v146, v146
	v_rcp_f32_e32 v147, v147
	v_rcp_f32_e32 v156, v156
	v_rcp_f32_e32 v207, v158
	s_mov_b64 s[8:9], 0

.LBB0_361:
	v_cvt_pk_bf16_f32 v138, v146, v156
	v_cvt_pk_bf16_f32 v139, v180, v208
	v_cvt_pk_bf16_f32 v140, v147, v179
	v_cvt_pk_bf16_f32 v141, v181, v207
	v_lshl_add_u64 v[136:137], v[136:137], 0, s[52:53]
	global_store_dwordx4 v[136:137], v[138:141], off offset:256
	v_pk_add_f32 v[142:143], v[34:35], v[222:223]
	v_pk_add_f32 v[144:145], v[32:33], v[220:221]
	v_pk_add_f32 v[138:139], v[38:39], v[218:219]
	v_pk_add_f32 v[140:141], v[36:37], v[216:217]
	s_cmp_gt_i32 s12, 1
	s_mov_b64 s[8:9], -1
	s_cbranch_scc0 .LBB0_363
	v_mul_f32_e32 v158, 0xbfb8aa3b, v145
	v_exp_f32_e32 v158, v158
	v_mul_f32_e32 v159, 0xbfb8aa3b, v138
	v_exp_f32_e32 v159, v159
	v_mul_f32_e32 v160, 0xbfb8aa3b, v142
	v_exp_f32_e32 v160, v160
	v_add_f32_e32 v158, 1.0, v158
	v_rcp_f32_e32 v179, v158
	v_add_f32_e32 v158, 1.0, v159
	v_mul_f32_e32 v159, 0xbfb8aa3b, v139
	v_mul_f32_e32 v146, 0xbfb8aa3b, v140
	v_mul_f32_e32 v147, 0xbfb8aa3b, v144
	v_mul_f32_e32 v156, 0xbfb8aa3b, v141
	v_rcp_f32_e32 v180, v158
	v_add_f32_e32 v158, 1.0, v160
	v_exp_f32_e32 v159, v159
	v_mul_f32_e32 v160, 0xbfb8aa3b, v143
	v_exp_f32_e32 v146, v146
	v_exp_f32_e32 v147, v147
	v_exp_f32_e32 v156, v156
	v_exp_f32_e32 v160, v160
	v_rcp_f32_e32 v181, v158
	v_add_f32_e32 v158, 1.0, v159
	v_add_f32_e32 v146, 1.0, v146
	v_add_f32_e32 v147, 1.0, v147
	v_add_f32_e32 v156, 1.0, v156
	v_rcp_f32_e32 v208, v158
	v_add_f32_e32 v158, 1.0, v160
	v_rcp_f32_e32 v146, v146
	v_rcp_f32_e32 v147, v147
	v_rcp_f32_e32 v156, v156
	v_rcp_f32_e32 v207, v158
	s_mov_b64 s[8:9], 0

.LBB0_367:
	v_cvt_pk_bf16_f32 v138, v146, v156
	v_cvt_pk_bf16_f32 v139, v180, v208
	v_cvt_pk_bf16_f32 v140, v147, v179
	v_cvt_pk_bf16_f32 v141, v181, v207
	v_lshl_add_u64 v[136:137], v[136:137], 0, s[52:53]
	global_store_dwordx4 v[136:137], v[138:141], off offset:256
	v_pk_add_f32 v[142:143], v[26:27], v[222:223]
	v_pk_add_f32 v[144:145], v[24:25], v[220:221]
	v_pk_add_f32 v[138:139], v[30:31], v[218:219]
	v_pk_add_f32 v[140:141], v[28:29], v[216:217]
	s_cmp_gt_i32 s12, 1
	s_mov_b64 s[8:9], -1
	s_cbranch_scc0 .LBB0_369
	v_mul_f32_e32 v158, 0xbfb8aa3b, v145
	v_exp_f32_e32 v158, v158
	v_mul_f32_e32 v159, 0xbfb8aa3b, v138
	v_exp_f32_e32 v159, v159
	v_mul_f32_e32 v160, 0xbfb8aa3b, v142
	v_exp_f32_e32 v160, v160
	v_add_f32_e32 v158, 1.0, v158
	v_rcp_f32_e32 v179, v158
	v_add_f32_e32 v158, 1.0, v159
	v_mul_f32_e32 v159, 0xbfb8aa3b, v139
	v_mul_f32_e32 v146, 0xbfb8aa3b, v140
	v_mul_f32_e32 v147, 0xbfb8aa3b, v144
	v_mul_f32_e32 v156, 0xbfb8aa3b, v141
	v_rcp_f32_e32 v180, v158
	v_add_f32_e32 v158, 1.0, v160
	v_exp_f32_e32 v159, v159
	v_mul_f32_e32 v160, 0xbfb8aa3b, v143
	v_exp_f32_e32 v146, v146
	v_exp_f32_e32 v147, v147
	v_exp_f32_e32 v156, v156
	v_exp_f32_e32 v160, v160
	v_rcp_f32_e32 v181, v158
	v_add_f32_e32 v158, 1.0, v159
	v_add_f32_e32 v146, 1.0, v146
	v_add_f32_e32 v147, 1.0, v147
	v_add_f32_e32 v156, 1.0, v156
	v_rcp_f32_e32 v208, v158
	v_add_f32_e32 v158, 1.0, v160
	v_rcp_f32_e32 v146, v146
	v_rcp_f32_e32 v147, v147
	v_rcp_f32_e32 v156, v156
	v_rcp_f32_e32 v207, v158
	s_mov_b64 s[8:9], 0

.LBB0_373:
	v_cvt_pk_bf16_f32 v138, v146, v156
	v_cvt_pk_bf16_f32 v139, v180, v208
	v_cvt_pk_bf16_f32 v140, v147, v179
	v_cvt_pk_bf16_f32 v141, v181, v207
	v_lshl_add_u64 v[136:137], v[136:137], 0, s[28:29]
	global_store_dwordx4 v[136:137], v[138:141], off offset:256
	v_pk_add_f32 v[142:143], v[18:19], v[222:223]
	v_pk_add_f32 v[144:145], v[16:17], v[220:221]
	v_pk_add_f32 v[138:139], v[22:23], v[218:219]
	v_pk_add_f32 v[140:141], v[20:21], v[216:217]
	s_cmp_gt_i32 s12, 1
	s_mov_b64 s[8:9], -1
	s_cbranch_scc0 .LBB0_375
	v_mul_f32_e32 v158, 0xbfb8aa3b, v145
	v_exp_f32_e32 v158, v158
	v_mul_f32_e32 v159, 0xbfb8aa3b, v138
	v_exp_f32_e32 v159, v159
	v_mul_f32_e32 v160, 0xbfb8aa3b, v142
	v_exp_f32_e32 v160, v160
	v_add_f32_e32 v158, 1.0, v158
	v_rcp_f32_e32 v179, v158
	v_add_f32_e32 v158, 1.0, v159
	v_mul_f32_e32 v159, 0xbfb8aa3b, v139
	v_mul_f32_e32 v146, 0xbfb8aa3b, v140
	v_mul_f32_e32 v147, 0xbfb8aa3b, v144
	v_mul_f32_e32 v156, 0xbfb8aa3b, v141
	v_rcp_f32_e32 v180, v158
	v_add_f32_e32 v158, 1.0, v160
	v_exp_f32_e32 v159, v159
	v_mul_f32_e32 v160, 0xbfb8aa3b, v143
	v_exp_f32_e32 v146, v146
	v_exp_f32_e32 v147, v147
	v_exp_f32_e32 v156, v156
	v_exp_f32_e32 v160, v160
	v_rcp_f32_e32 v181, v158
	v_add_f32_e32 v158, 1.0, v159
	v_add_f32_e32 v146, 1.0, v146
	v_add_f32_e32 v147, 1.0, v147
	v_add_f32_e32 v156, 1.0, v156
	v_rcp_f32_e32 v208, v158
	v_add_f32_e32 v158, 1.0, v160
	v_rcp_f32_e32 v146, v146
	v_rcp_f32_e32 v147, v147
	v_rcp_f32_e32 v156, v156
	v_rcp_f32_e32 v207, v158
	s_mov_b64 s[8:9], 0

.LBB0_379:
	v_cvt_pk_bf16_f32 v138, v146, v156
	v_cvt_pk_bf16_f32 v139, v180, v208
	v_cvt_pk_bf16_f32 v140, v147, v179
	v_cvt_pk_bf16_f32 v141, v181, v207
	v_lshl_add_u64 v[136:137], v[136:137], 0, s[52:53]
	global_store_dwordx4 v[136:137], v[138:141], off offset:256
	v_pk_add_f32 v[142:143], v[10:11], v[222:223]
	v_pk_add_f32 v[144:145], v[8:9], v[220:221]
	v_pk_add_f32 v[138:139], v[14:15], v[218:219]
	v_pk_add_f32 v[140:141], v[12:13], v[216:217]
	s_cmp_gt_i32 s12, 1
	s_mov_b64 s[8:9], -1
	s_cbranch_scc0 .LBB0_381
	v_mul_f32_e32 v158, 0xbfb8aa3b, v145
	v_exp_f32_e32 v158, v158
	v_mul_f32_e32 v159, 0xbfb8aa3b, v138
	v_exp_f32_e32 v159, v159
	v_mul_f32_e32 v160, 0xbfb8aa3b, v142
	v_exp_f32_e32 v160, v160
	v_add_f32_e32 v158, 1.0, v158
	v_rcp_f32_e32 v179, v158
	v_add_f32_e32 v158, 1.0, v159
	v_mul_f32_e32 v159, 0xbfb8aa3b, v139
	v_mul_f32_e32 v146, 0xbfb8aa3b, v140
	v_mul_f32_e32 v147, 0xbfb8aa3b, v144
	v_mul_f32_e32 v156, 0xbfb8aa3b, v141
	v_rcp_f32_e32 v180, v158
	v_add_f32_e32 v158, 1.0, v160
	v_exp_f32_e32 v159, v159
	v_mul_f32_e32 v160, 0xbfb8aa3b, v143
	v_exp_f32_e32 v146, v146
	v_exp_f32_e32 v147, v147
	v_exp_f32_e32 v156, v156
	v_exp_f32_e32 v160, v160
	v_rcp_f32_e32 v181, v158
	v_add_f32_e32 v158, 1.0, v159
	v_add_f32_e32 v146, 1.0, v146
	v_add_f32_e32 v147, 1.0, v147
	v_add_f32_e32 v156, 1.0, v156
	v_rcp_f32_e32 v208, v158
	v_add_f32_e32 v158, 1.0, v160
	v_rcp_f32_e32 v146, v146
	v_rcp_f32_e32 v147, v147
	v_rcp_f32_e32 v156, v156
	v_rcp_f32_e32 v207, v158
	s_mov_b64 s[8:9], 0

.LBB0_385:
	v_cvt_pk_bf16_f32 v138, v146, v156
	v_cvt_pk_bf16_f32 v139, v180, v208
	v_cvt_pk_bf16_f32 v140, v147, v179
	v_cvt_pk_bf16_f32 v141, v181, v207
	v_lshl_add_u64 v[136:137], v[136:137], 0, s[52:53]
	v_pk_add_f32 v[134:135], v[6:7], v[218:219]
	v_pk_add_f32 v[132:133], v[4:5], v[216:217]
	v_pk_add_f32 v[130:131], v[2:3], v[222:223]
	v_pk_add_f32 v[128:129], v[0:1], v[220:221]
	s_cmp_gt_i32 s12, 1
	s_mov_b64 s[8:9], -1
	global_store_dwordx4 v[136:137], v[138:141], off offset:256
	s_cbranch_scc0 .LBB0_387
	v_mul_f32_e32 v144, 0xbfb8aa3b, v135
	v_mul_f32_e32 v138, 0xbfb8aa3b, v132
	v_mul_f32_e32 v139, 0xbfb8aa3b, v128
	v_mul_f32_e32 v140, 0xbfb8aa3b, v133
	v_mul_f32_e32 v141, 0xbfb8aa3b, v129
	v_mul_f32_e32 v142, 0xbfb8aa3b, v134
	v_mul_f32_e32 v143, 0xbfb8aa3b, v130
	v_exp_f32_e32 v144, v144
	v_mul_f32_e32 v145, 0xbfb8aa3b, v131
	v_exp_f32_e32 v138, v138
	v_exp_f32_e32 v139, v139
	v_exp_f32_e32 v140, v140
	v_exp_f32_e32 v141, v141
	v_exp_f32_e32 v142, v142
	v_exp_f32_e32 v143, v143
	v_exp_f32_e32 v146, v145
	v_add_f32_e32 v144, 1.0, v144
	v_add_f32_e32 v138, 1.0, v138
	v_add_f32_e32 v139, 1.0, v139
	v_add_f32_e32 v140, 1.0, v140
	v_add_f32_e32 v141, 1.0, v141
	v_add_f32_e32 v142, 1.0, v142
	v_add_f32_e32 v143, 1.0, v143
	v_rcp_f32_e32 v145, v144
	v_add_f32_e32 v144, 1.0, v146
	v_rcp_f32_e32 v138, v138
	v_rcp_f32_e32 v139, v139
	v_rcp_f32_e32 v140, v140
	v_rcp_f32_e32 v141, v141
	v_rcp_f32_e32 v142, v142
	v_rcp_f32_e32 v143, v143
	v_rcp_f32_e32 v144, v144
	s_mov_b64 s[8:9], 0
